# Fourier column items (phase 6): next item's transposing loads prefetched during the current item's MFMAs, counted head waits; plus twiddle hoist
# speedup vs baseline: 1.0035x; 1.0035x over previous
.LBB0_595:
	s_cmpk_gt_i32 s2, 0x7ff
	s_cbranch_scc1 .LBB0_602
	v_bfe_u32 v4, v146, 4, 2
	v_lshlrev_b32_e32 v0, 4, v4
	v_mov_b32_e32 v1, 0
	v_lshlrev_b32_e32 v6, 4, v195
	v_lshl_add_u64 v[2:3], s[34:35], 0, v[0:1]
	v_add_u32_e32 v5, 0, v0
	v_or_b32_e32 v0, v6, v181
	s_movk_i32 s0, 0x200
	v_lshlrev_b32_e32 v0, 8, v0
	v_cmp_gt_u32_e64 s[6:7], s0, v146
	v_lshlrev_b32_e32 v4, 2, v4
	v_lshl_add_u64 v[2:3], v[2:3], 0, v[0:1]
	s_mov_b64 s[0:1], 0x3140000
	v_mul_u32_u24_e32 v0, 0x110, v181
	v_lshlrev_b32_e32 v7, 5, v195
	v_lshl_add_u64 v[2:3], v[2:3], 0, s[0:1]
	s_and_saveexec_b64 s[16:17], s[6:7]
	global_load_dwordx4 v[124:127], v[2:3], off
	global_load_dwordx4 v[128:131], v[2:3], off offset:64
	global_load_dwordx4 v[132:135], v[2:3], off offset:128
	global_load_dwordx4 v[136:139], v[2:3], off offset:192
	s_or_b64 exec, exec, s[16:17]
	s_movk_i32 s3, 0x110
	v_bitop3_b32 v6, v6, 63, v181 bitop3:0xc8
	v_and_b32_e32 v7, 0x80, v7
	v_add_u32_e32 v8, 0xfffffe00, v146
	v_lshlrev_b32_e32 v9, 1, v146
	s_mov_b32 s4, 0xffff0000
	v_add_u32_e32 v10, v5, v0
	v_lshlrev_b32_e32 v4, 1, v4
	s_mov_b32 s5, s2
	v_and_b32_e32 v106, 62, v9
	v_and_b32_e32 v107, 0x80, v101
	v_and_b32_e32 v108, 0x78, v101
	v_lshlrev_b32_e32 v96, 11, v106
	v_lshl_add_u32 v96, v107, 1, v96
	v_lshl_add_u32 v96, v108, 1, v96
	v_mad_u32_u24 v97, v108, s3, 0
	v_lshlrev_b32_e32 v106, 1, v106
	v_add3_u32 v97, v97, v107, v106
	v_add_u32_e32 v98, 0x400, v97
	v_add_u32_e32 v99, 0x80, v97
	v_add_u32_e32 v100, 0x480, v97
	s_lshl_b32 s20, s5, 4
	s_and_b32 s20, s20, 0xffffffc0
	s_addk_i32 s20, 0x2000
	s_lshl_b32 s21, s5, 8
	s_and_b32 s21, s21, 0x300
	s_lshl_b32 s21, s21, 1
	s_lshl_b32 s20, s20, 11
	s_add_u32 s18, s58, s21
	s_addc_u32 s19, s59, 0
	s_add_u32 s18, s18, s20
	s_addc_u32 s19, s19, 0
	global_load_dwordx4 v[102:105], v96, s[18:19]
	global_load_dwordx4 v[110:113], v96, s[18:19] offset:2048
	global_load_dwordx4 v[114:117], v96, s[18:19] offset:256
	global_load_dwordx4 v[140:143], v96, s[18:19] offset:2304
	s_waitcnt vmcnt(0)
	s_branch .LBB0_598

.LBB0_598:
	s_lshl_b32 s0, s5, 4
	s_and_b32 s10, s0, 0xffffffc0
	s_lshl_b32 s0, s5, 8
	s_and_b32 s11, s0, 0x300
	s_addk_i32 s10, 0x2000
	s_lshl_b32 s0, s11, 1
	s_add_u32 s0, s58, s0
	s_addc_u32 s1, s59, 0
	s_mov_b64 s[8:9], 0
	s_waitcnt vmcnt(11)
	v_and_b32_e32 v22, 0xffff, v102
	v_lshrrev_b32_e32 v102, 16, v102
	v_and_b32_e32 v23, 0xffff, v103
	v_lshrrev_b32_e32 v103, 16, v103
	v_and_b32_e32 v24, 0xffff, v104
	v_lshrrev_b32_e32 v104, 16, v104
	v_and_b32_e32 v25, 0xffff, v105
	v_lshrrev_b32_e32 v105, 16, v105
	s_waitcnt vmcnt(10)
	v_lshl_or_b32 v22, v110, 16, v22
	v_and_or_b32 v102, v110, s4, v102
	v_lshl_or_b32 v110, v111, 16, v23
	v_and_or_b32 v103, v111, s4, v103
	v_lshl_or_b32 v111, v112, 16, v24
	v_and_or_b32 v104, v112, s4, v104
	v_lshl_or_b32 v112, v113, 16, v25
	v_and_or_b32 v105, v113, s4, v105
	ds_write2_b32 v97, v22, v102 offset1:68
	ds_write2_b32 v97, v110, v103 offset0:136 offset1:204
	ds_write2_b32 v98, v111, v104 offset0:16 offset1:84
	ds_write2_b32 v98, v112, v105 offset0:152 offset1:220
	s_waitcnt vmcnt(9)
	v_and_b32_e32 v38, 0xffff, v114
	v_lshrrev_b32_e32 v114, 16, v114
	v_and_b32_e32 v39, 0xffff, v115
	v_lshrrev_b32_e32 v115, 16, v115
	v_and_b32_e32 v40, 0xffff, v116
	v_lshrrev_b32_e32 v116, 16, v116
	v_and_b32_e32 v41, 0xffff, v117
	v_lshrrev_b32_e32 v117, 16, v117
	s_waitcnt vmcnt(8)
	v_lshl_or_b32 v38, v140, 16, v38
	v_and_or_b32 v114, v140, s4, v114
	v_lshl_or_b32 v140, v141, 16, v39
	v_and_or_b32 v115, v141, s4, v115
	v_lshl_or_b32 v141, v142, 16, v40
	v_and_or_b32 v116, v142, s4, v116
	v_lshl_or_b32 v142, v143, 16, v41
	v_and_or_b32 v117, v143, s4, v117
	ds_write2_b32 v99, v38, v114 offset1:68
	ds_write2_b32 v99, v140, v115 offset0:136 offset1:204
	ds_write2_b32 v100, v141, v116 offset0:16 offset1:84
	ds_write2_b32 v100, v142, v117 offset0:152 offset1:220
	s_waitcnt lgkmcnt(0)
	s_barrier
	s_add_i32 s22, s5, s68
	s_cmpk_lt_i32 s22, 0x800
	s_cbranch_scc0 .Lfc_nopf
	s_lshl_b32 s20, s22, 4
	s_and_b32 s20, s20, 0xffffffc0
	s_addk_i32 s20, 0x2000
	s_lshl_b32 s21, s22, 8
	s_and_b32 s21, s21, 0x300
	s_lshl_b32 s21, s21, 1
	s_lshl_b32 s20, s20, 11
	s_add_u32 s18, s58, s21
	s_addc_u32 s19, s59, 0
	s_add_u32 s18, s18, s20
	s_addc_u32 s19, s19, 0
	global_load_dwordx4 v[102:105], v96, s[18:19]
	global_load_dwordx4 v[110:113], v96, s[18:19] offset:2048
	global_load_dwordx4 v[114:117], v96, s[18:19] offset:256
	global_load_dwordx4 v[140:143], v96, s[18:19] offset:2304
.Lfc_nopf:
	s_and_saveexec_b64 s[0:1], s[6:7]
	s_cbranch_execz .LBB0_597
	ds_read_b128 v[16:19], v10
	ds_read_b128 v[24:27], v10 offset:64
	ds_read_b128 v[28:31], v10 offset:4352
	ds_read_b128 v[32:35], v10 offset:4416
	ds_read_b128 v[36:39], v10 offset:8704
	ds_read_b128 v[40:43], v10 offset:8768
	ds_read_b128 v[44:47], v10 offset:13056
	ds_read_b128 v[48:51], v10 offset:13120
	ds_read_b128 v[52:55], v10 offset:17408
	ds_read_b128 v[56:59], v10 offset:17472
	ds_read_b128 v[60:63], v10 offset:21760
	ds_read_b128 v[64:67], v10 offset:21824
	ds_read_b128 v[68:71], v10 offset:26112
	ds_read_b128 v[72:75], v10 offset:26176
	ds_read_b128 v[76:79], v10 offset:30464
	ds_read_b128 v[80:83], v10 offset:30528
	v_or_b32_e32 v0, s11, v7
	v_lshlrev_b32_e32 v0, 1, v0
	v_mov_b32_e32 v5, v1
	s_waitcnt lgkmcnt(14)
	v_mfma_f32_16x16x32_bf16 v[16:19], v[16:19], v[124:127], 0
	s_waitcnt lgkmcnt(13)
	v_mfma_f32_16x16x32_bf16 v[28:31], v[28:31], v[124:127], 0
	s_waitcnt lgkmcnt(11)
	v_mfma_f32_16x16x32_bf16 v[36:39], v[36:39], v[124:127], 0
	v_mfma_f32_16x16x32_bf16 v[16:19], v[24:27], v[128:131], v[16:19]
	v_mfma_f32_16x16x32_bf16 v[24:27], v[32:35], v[128:131], v[28:31]
	s_waitcnt lgkmcnt(10)
	v_mfma_f32_16x16x32_bf16 v[28:31], v[40:43], v[128:131], v[36:39]
	s_waitcnt lgkmcnt(9)
	v_mfma_f32_16x16x32_bf16 v[44:47], v[44:47], v[124:127], 0
	s_waitcnt lgkmcnt(8)
	v_mfma_f32_16x16x32_bf16 v[32:35], v[48:51], v[128:131], v[44:47]
	s_waitcnt lgkmcnt(7)
	v_mfma_f32_16x16x32_bf16 v[52:55], v[52:55], v[124:127], 0
	s_waitcnt lgkmcnt(6)
	v_mfma_f32_16x16x32_bf16 v[36:39], v[56:59], v[128:131], v[52:55]
	ds_read_b128 v[56:59], v10 offset:128
	s_waitcnt lgkmcnt(6)
	v_mfma_f32_16x16x32_bf16 v[60:63], v[60:63], v[124:127], 0
	s_waitcnt lgkmcnt(4)
	v_mfma_f32_16x16x32_bf16 v[68:71], v[68:71], v[124:127], 0
	s_waitcnt lgkmcnt(2)
	v_mfma_f32_16x16x32_bf16 v[12:15], v[76:79], v[124:127], 0
	v_mfma_f32_16x16x32_bf16 v[44:47], v[64:67], v[128:131], v[60:63]
	v_mfma_f32_16x16x32_bf16 v[52:55], v[72:75], v[128:131], v[68:71]
	s_waitcnt lgkmcnt(1)
	v_mfma_f32_16x16x32_bf16 v[12:15], v[80:83], v[128:131], v[12:15]
	ds_read_b128 v[20:23], v10 offset:4480
	ds_read_b128 v[60:63], v10 offset:192
	s_waitcnt lgkmcnt(2)
	v_mfma_f32_16x16x32_bf16 v[16:19], v[56:59], v[132:135], v[16:19]
	ds_read_b128 v[56:59], v10 offset:8832
	ds_read_b128 v[64:67], v10 offset:4544
	s_waitcnt lgkmcnt(3)
	v_mfma_f32_16x16x32_bf16 v[20:23], v[20:23], v[132:135], v[24:27]
	s_nop 2
	ds_read_b128 v[24:27], v10 offset:13184
	ds_read_b128 v[68:71], v10 offset:8896
	s_waitcnt lgkmcnt(3)
	v_mfma_f32_16x16x32_bf16 v[28:31], v[56:59], v[132:135], v[28:31]
	ds_read_b128 v[56:59], v10 offset:17536
	ds_read_b128 v[72:75], v10 offset:21888
	ds_read_b128 v[76:79], v10 offset:13248
	s_waitcnt lgkmcnt(4)
	v_mfma_f32_16x16x32_bf16 v[24:27], v[24:27], v[132:135], v[32:35]
	s_nop 2
	ds_read_b128 v[32:35], v10 offset:26240
	ds_read_b128 v[80:83], v10 offset:17600
	ds_read_b128 v[84:87], v10 offset:21952
	s_waitcnt lgkmcnt(5)
	v_mfma_f32_16x16x32_bf16 v[36:39], v[56:59], v[132:135], v[36:39]
	ds_read_b128 v[56:59], v10 offset:26304
	ds_read_b128 v[88:91], v10 offset:30592
	ds_read_b128 v[92:95], v10 offset:30656
	s_waitcnt lgkmcnt(7)
	v_mfma_f32_16x16x32_bf16 v[44:47], v[72:75], v[132:135], v[44:47]
	v_or_b32_e32 v72, s10, v6
	v_ashrrev_i32_e32 v73, 31, v72
	v_mfma_f32_16x16x32_bf16 v[16:19], v[60:63], v[136:139], v[16:19]
	s_waitcnt lgkmcnt(5)
	v_mfma_f32_16x16x32_bf16 v[32:35], v[32:35], v[132:135], v[52:55]
	s_nop 2
	v_lshlrev_b64 v[52:53], 11, v[72:73]
	v_lshl_add_u64 v[52:53], s[58:59], 0, v[52:53]
	s_waitcnt lgkmcnt(1)
	v_mfma_f32_16x16x32_bf16 v[12:15], v[88:91], v[132:135], v[12:15]
	v_lshl_add_u64 v[40:41], v[52:53], 0, v[0:1]
	v_lshl_add_u64 v[40:41], v[40:41], 0, v[4:5]
	v_cvt_pk_bf16_f32 v16, v16, v17
	v_cvt_pk_bf16_f32 v17, v18, v19
	global_store_dwordx2 v[40:41], v[16:17], off
	v_mfma_f32_16x16x32_bf16 v[16:19], v[64:67], v[136:139], v[20:23]
	s_waitcnt lgkmcnt(0)
	v_mfma_f32_16x16x32_bf16 v[12:15], v[92:95], v[136:139], v[12:15]
	s_nop 5
	v_cvt_pk_bf16_f32 v16, v16, v17
	v_cvt_pk_bf16_f32 v17, v18, v19
	global_store_dwordx2 v[40:41], v[16:17], off offset:32
	v_mfma_f32_16x16x32_bf16 v[16:19], v[68:71], v[136:139], v[28:31]
	v_cvt_pk_bf16_f32 v12, v12, v13
	v_cvt_pk_bf16_f32 v13, v14, v15
	global_store_dwordx2 v[40:41], v[12:13], off offset:224
	s_nop 4
	v_cvt_pk_bf16_f32 v16, v16, v17
	v_cvt_pk_bf16_f32 v17, v18, v19
	global_store_dwordx2 v[40:41], v[16:17], off offset:64
	v_mfma_f32_16x16x32_bf16 v[16:19], v[76:79], v[136:139], v[24:27]
	s_nop 7
	v_cvt_pk_bf16_f32 v16, v16, v17
	v_cvt_pk_bf16_f32 v17, v18, v19
	global_store_dwordx2 v[40:41], v[16:17], off offset:96
	v_mfma_f32_16x16x32_bf16 v[16:19], v[80:83], v[136:139], v[36:39]
	s_nop 7
	v_cvt_pk_bf16_f32 v16, v16, v17
	v_cvt_pk_bf16_f32 v17, v18, v19
	global_store_dwordx2 v[40:41], v[16:17], off offset:128
	v_mfma_f32_16x16x32_bf16 v[16:19], v[84:87], v[136:139], v[44:47]
	s_nop 7
	v_cvt_pk_bf16_f32 v16, v16, v17
	v_cvt_pk_bf16_f32 v17, v18, v19
	global_store_dwordx2 v[40:41], v[16:17], off offset:160
	v_mfma_f32_16x16x32_bf16 v[16:19], v[56:59], v[136:139], v[32:35]
	s_nop 7
	v_cvt_pk_bf16_f32 v16, v16, v17
	v_cvt_pk_bf16_f32 v17, v18, v19
	global_store_dwordx2 v[40:41], v[16:17], off offset:192
	s_branch .LBB0_597
